# grid-barrier spin loops: polling interval s_sleep 1 -> s_sleep 0 (55 sites)
# speedup vs baseline: 1.0063x; 1.0063x over previous
.LBB0_152:
	s_sleep 0
	global_load_dword v2, v0, s[6:7] offset:32 sc1
	s_waitcnt vmcnt(0)
	v_and_b32_e32 v2, 0xffff0000, v2
	v_cmp_ne_u32_e32 vcc, v2, v1
	s_or_b64 s[8:9], vcc, s[8:9]
	s_andn2_b64 exec, exec, s[8:9]
	s_cbranch_execnz .LBB0_152

; DI unsigned xb_ld(unsigned* p)              { return __hip_atomic_load(p, __ATOMIC_RELAXED, __HIP_MEMORY_SCOPE_AGENT); }
; DI void xcd_barrier_complete(unsigned* bar, unsigned x, unsigned& nloc, unsigned& nx) {
;     const unsigned G = gridDim.x * gridDim.y * gridDim.z;
;     unsigned sum, cnt, mine, sp = 0u;
;     for (;;) {
;         sum = 0u; cnt = 0u; mine = 0u;
; #pragma unroll
;         for (unsigned j = 0; j < 16; ++j) { const unsigned c = xb_ld(&bar[XB_XCNT(j)]); sum += c; cnt += (c > 0u) ? 1u : 0u; mine = (j == x) ? c : mine; }
;         if (sum == G) break;
;         __builtin_amdgcn_s_sleep(1);
;         if ((++sp & 255u) == 0u) { if (xb_ld(&bar[XB_TMO])) break; if (sp > XB_SPIN_CAP) { atomicAdd(&bar[XB_TMO], 1u); break; } }
;     }
.LBB0_295:
	global_load_dword v15, v16, s[94:95] offset:1024 sc1
	s_waitcnt lgkmcnt(0)
	global_load_dword v0, v16, s[94:95] offset:1280 sc1
	global_load_dword v1, v16, s[94:95] offset:1536 sc1
	global_load_dword v2, v16, s[94:95] offset:1792 sc1
	global_load_dword v3, v16, s[94:95] offset:2048 sc1
	global_load_dword v4, v16, s[94:95] offset:2304 sc1
	global_load_dword v5, v16, s[94:95] offset:2560 sc1
	global_load_dword v6, v16, s[94:95] offset:2816 sc1
	global_load_dword v7, v16, s[94:95] offset:3072 sc1
	global_load_dword v8, v16, s[94:95] offset:3328 sc1
	global_load_dword v9, v16, s[94:95] offset:3584 sc1
	global_load_dword v10, v16, s[94:95] offset:3840 sc1
	global_load_dword v11, v16, s[4:5] sc1
	global_load_dword v12, v16, s[6:7] sc1
	global_load_dword v13, v16, s[8:9] sc1
	global_load_dword v14, v16, s[10:11] sc1
	s_mov_b64 s[12:13], -1
	s_mov_b64 s[14:15], -1
	s_waitcnt vmcnt(14)
	v_add_u32_e32 v17, v0, v15
	s_waitcnt vmcnt(13)
	v_add_u32_e32 v17, v17, v1
	s_waitcnt vmcnt(12)
	v_add_u32_e32 v17, v17, v2
	s_waitcnt vmcnt(11)
	v_add_u32_e32 v17, v17, v3
	s_waitcnt vmcnt(10)
	v_add_u32_e32 v17, v17, v4
	s_waitcnt vmcnt(9)
	v_add_u32_e32 v17, v17, v5
	s_waitcnt vmcnt(8)
	v_add_u32_e32 v17, v17, v6
	s_waitcnt vmcnt(7)
	v_add_u32_e32 v17, v17, v7
	s_waitcnt vmcnt(6)
	v_add_u32_e32 v17, v17, v8
	s_waitcnt vmcnt(5)
	v_add_u32_e32 v17, v17, v9
	s_waitcnt vmcnt(4)
	v_add_u32_e32 v17, v17, v10
	s_waitcnt vmcnt(3)
	v_add_u32_e32 v17, v17, v11
	s_waitcnt vmcnt(2)
	v_add_u32_e32 v17, v17, v12
	s_waitcnt vmcnt(1)
	v_add_u32_e32 v17, v17, v13
	s_waitcnt vmcnt(0)
	v_add_u32_e32 v17, v17, v14
	v_cmp_eq_u32_e32 vcc, s2, v17
	s_cbranch_vccnz .LBB0_294
	s_and_b32 s12, s3, 0xff
	s_cmp_eq_u32 s12, 0
	s_mov_b64 s[12:13], -1
	s_mov_b64 s[16:17], -1
	s_sleep 0
	s_cbranch_scc1 .LBB0_299
	s_and_b64 vcc, exec, s[16:17]
	s_cbranch_vccz .LBB0_294

; DI unsigned xb_ld(unsigned* p)              { return __hip_atomic_load(p, __ATOMIC_RELAXED, __HIP_MEMORY_SCOPE_AGENT); }
; #define XB_SPIN(cond, bar) do { unsigned _sp = 0; while (cond) { __builtin_amdgcn_s_sleep(1); \
;     if ((++_sp & 255u) == 0u) { if (xb_ld(&(bar)[XB_TMO])) break; if (_sp > XB_SPIN_CAP) { atomicAdd(&(bar)[XB_TMO], 1u); break; } } } } while (0)
; DI void xcd_barrier(const XcdBarrier& b) {
;     ...
;             else XB_SPIN(xb_ld(&bar[XB_TOPGEN]) == tg, bar);
;     ...
;             XB_SPIN(xb_ld(&bar[XB_XGEN(b.x)]) == gen, bar);
.LBB0_309:
	s_and_b32 s3, s2, 0xff
	s_mov_b64 s[16:17], -1
	s_cmp_lg_u32 s3, 0
	s_mov_b64 s[20:21], -1
	s_sleep 0
	s_cbranch_scc0 .LBB0_312
	s_and_b64 vcc, exec, s[20:21]
	s_cbranch_vccz .LBB0_308

; DI unsigned xb_ld(unsigned* p)              { return __hip_atomic_load(p, __ATOMIC_RELAXED, __HIP_MEMORY_SCOPE_AGENT); }
; #define XB_SPIN(cond, bar) do { unsigned _sp = 0; while (cond) { __builtin_amdgcn_s_sleep(1); \
;     if ((++_sp & 255u) == 0u) { if (xb_ld(&(bar)[XB_TMO])) break; if (_sp > XB_SPIN_CAP) { atomicAdd(&(bar)[XB_TMO], 1u); break; } } } } while (0)
; DI void xcd_barrier(const XcdBarrier& b) {
;     ...
;             XB_SPIN(xb_ld(&bar[XB_XGEN(b.x)]) == gen, bar);
.LBB0_323:
	s_and_b32 s3, s2, 0xff
	s_cmp_lg_u32 s3, 0
	s_mov_b64 s[20:21], -1
	s_sleep 0
	s_cbranch_scc0 .LBB0_326
	s_mov_b64 s[22:23], -1
	s_and_b64 vcc, exec, s[20:21]
	s_cbranch_vccz .LBB0_322

; DI unsigned xb_ld(unsigned* p)              { return __hip_atomic_load(p, __ATOMIC_RELAXED, __HIP_MEMORY_SCOPE_AGENT); }
; DI void xcd_barrier_complete(unsigned* bar, unsigned x, unsigned& nloc, unsigned& nx) {
;     const unsigned G = gridDim.x * gridDim.y * gridDim.z;
;     unsigned sum, cnt, mine, sp = 0u;
;     for (;;) {
;         sum = 0u; cnt = 0u; mine = 0u;
; #pragma unroll
;         for (unsigned j = 0; j < 16; ++j) { const unsigned c = xb_ld(&bar[XB_XCNT(j)]); sum += c; cnt += (c > 0u) ? 1u : 0u; mine = (j == x) ? c : mine; }
;         if (sum == G) break;
;         __builtin_amdgcn_s_sleep(1);
;         if ((++sp & 255u) == 0u) { if (xb_ld(&bar[XB_TMO])) break; if (sp > XB_SPIN_CAP) { atomicAdd(&bar[XB_TMO], 1u); break; } }
;     }
.LBB0_713:
	global_load_dword v15, v16, s[94:95] offset:1024 sc1
	s_waitcnt lgkmcnt(0)
	global_load_dword v0, v16, s[94:95] offset:1280 sc1
	global_load_dword v1, v16, s[94:95] offset:1536 sc1
	global_load_dword v2, v16, s[94:95] offset:1792 sc1
	global_load_dword v3, v16, s[94:95] offset:2048 sc1
	global_load_dword v4, v16, s[94:95] offset:2304 sc1
	global_load_dword v5, v16, s[94:95] offset:2560 sc1
	global_load_dword v6, v16, s[94:95] offset:2816 sc1
	global_load_dword v7, v16, s[94:95] offset:3072 sc1
	global_load_dword v8, v16, s[94:95] offset:3328 sc1
	global_load_dword v9, v16, s[94:95] offset:3584 sc1
	global_load_dword v10, v16, s[94:95] offset:3840 sc1
	global_load_dword v11, v16, s[8:9] sc1
	global_load_dword v12, v16, s[34:35] sc1
	global_load_dword v13, v16, s[36:37] sc1
	global_load_dword v14, v16, s[38:39] sc1
	s_mov_b64 s[40:41], -1
	s_mov_b64 s[42:43], -1
	s_waitcnt vmcnt(14)
	v_add_u32_e32 v17, v0, v15
	s_waitcnt vmcnt(13)
	v_add_u32_e32 v17, v17, v1
	s_waitcnt vmcnt(12)
	v_add_u32_e32 v17, v17, v2
	s_waitcnt vmcnt(11)
	v_add_u32_e32 v17, v17, v3
	s_waitcnt vmcnt(10)
	v_add_u32_e32 v17, v17, v4
	s_waitcnt vmcnt(9)
	v_add_u32_e32 v17, v17, v5
	s_waitcnt vmcnt(8)
	v_add_u32_e32 v17, v17, v6
	s_waitcnt vmcnt(7)
	v_add_u32_e32 v17, v17, v7
	s_waitcnt vmcnt(6)
	v_add_u32_e32 v17, v17, v8
	s_waitcnt vmcnt(5)
	v_add_u32_e32 v17, v17, v9
	s_waitcnt vmcnt(4)
	v_add_u32_e32 v17, v17, v10
	s_waitcnt vmcnt(3)
	v_add_u32_e32 v17, v17, v11
	s_waitcnt vmcnt(2)
	v_add_u32_e32 v17, v17, v12
	s_waitcnt vmcnt(1)
	v_add_u32_e32 v17, v17, v13
	s_waitcnt vmcnt(0)
	v_add_u32_e32 v17, v17, v14
	v_cmp_eq_u32_e32 vcc, s2, v17
	s_cbranch_vccnz .LBB0_712
	s_and_b32 s40, s33, 0xff
	s_cmp_eq_u32 s40, 0
	s_mov_b64 s[40:41], -1
	s_mov_b64 s[44:45], -1
	s_sleep 0
	s_cbranch_scc1 .LBB0_717
	s_and_b64 vcc, exec, s[44:45]
	s_cbranch_vccz .LBB0_712

; DI unsigned xb_ld(unsigned* p)              { return __hip_atomic_load(p, __ATOMIC_RELAXED, __HIP_MEMORY_SCOPE_AGENT); }
; #define XB_SPIN(cond, bar) do { unsigned _sp = 0; while (cond) { __builtin_amdgcn_s_sleep(1); \
;     if ((++_sp & 255u) == 0u) { if (xb_ld(&(bar)[XB_TMO])) break; if (_sp > XB_SPIN_CAP) { atomicAdd(&(bar)[XB_TMO], 1u); break; } } } } while (0)
; DI void xcd_barrier(const XcdBarrier& b) {
;     ...
;             else XB_SPIN(xb_ld(&bar[XB_TOPGEN]) == tg, bar);
.LBB0_727:
	s_and_b32 s33, s2, 0xff
	s_mov_b64 s[42:43], -1
	s_cmp_lg_u32 s33, 0
	s_mov_b64 s[46:47], -1
	s_sleep 0
	s_cbranch_scc0 .LBB0_730
	s_and_b64 vcc, exec, s[46:47]
	s_cbranch_vccz .LBB0_726

; DI unsigned xb_ld(unsigned* p)              { return __hip_atomic_load(p, __ATOMIC_RELAXED, __HIP_MEMORY_SCOPE_AGENT); }
; #define XB_SPIN(cond, bar) do { unsigned _sp = 0; while (cond) { __builtin_amdgcn_s_sleep(1); \
;     if ((++_sp & 255u) == 0u) { if (xb_ld(&(bar)[XB_TMO])) break; if (_sp > XB_SPIN_CAP) { atomicAdd(&(bar)[XB_TMO], 1u); break; } } } } while (0)
; DI void xcd_barrier(const XcdBarrier& b) {
;     ...
;             XB_SPIN(xb_ld(&bar[XB_XGEN(b.x)]) == gen, bar);
.LBB0_741:
	s_and_b32 s33, s2, 0xff
	s_cmp_lg_u32 s33, 0
	s_mov_b64 s[46:47], -1
	s_sleep 0
	s_cbranch_scc0 .LBB0_744
	s_mov_b64 s[48:49], -1
	s_and_b64 vcc, exec, s[46:47]
	s_cbranch_vccz .LBB0_740

; DI unsigned xb_ld(unsigned* p)              { return __hip_atomic_load(p, __ATOMIC_RELAXED, __HIP_MEMORY_SCOPE_AGENT); }
; DI void xcd_barrier_complete(unsigned* bar, unsigned x, unsigned& nloc, unsigned& nx) {
;     const unsigned G = gridDim.x * gridDim.y * gridDim.z;
;     unsigned sum, cnt, mine, sp = 0u;
;     for (;;) {
;         sum = 0u; cnt = 0u; mine = 0u;
; #pragma unroll
;         for (unsigned j = 0; j < 16; ++j) { const unsigned c = xb_ld(&bar[XB_XCNT(j)]); sum += c; cnt += (c > 0u) ? 1u : 0u; mine = (j == x) ? c : mine; }
;         if (sum == G) break;
;         __builtin_amdgcn_s_sleep(1);
;         if ((++sp & 255u) == 0u) { if (xb_ld(&bar[XB_TMO])) break; if (sp > XB_SPIN_CAP) { atomicAdd(&bar[XB_TMO], 1u); break; } }
;     }
.LBB0_1479:
	global_load_dword v24, v2, s[94:95] offset:1024 sc1
	s_waitcnt lgkmcnt(0)
	global_load_dword v0, v2, s[94:95] offset:1280 sc1
	global_load_dword v1, v2, s[94:95] offset:1536 sc1
	global_load_dword v3, v2, s[94:95] offset:1792 sc1
	global_load_dword v12, v2, s[94:95] offset:2048 sc1
	global_load_dword v13, v2, s[94:95] offset:2304 sc1
	global_load_dword v14, v2, s[94:95] offset:2560 sc1
	global_load_dword v15, v2, s[94:95] offset:2816 sc1
	global_load_dword v16, v2, s[94:95] offset:3072 sc1
	global_load_dword v17, v2, s[94:95] offset:3328 sc1
	global_load_dword v18, v2, s[94:95] offset:3584 sc1
	global_load_dword v19, v2, s[94:95] offset:3840 sc1
	global_load_dword v20, v2, s[70:71] sc1
	global_load_dword v21, v2, s[72:73] sc1
	global_load_dword v22, v2, s[74:75] sc1
	global_load_dword v23, v2, s[76:77] sc1
	s_mov_b64 s[10:11], -1
	s_mov_b64 s[12:13], -1
	s_waitcnt vmcnt(14)
	v_add_u32_e32 v25, v0, v24
	s_waitcnt vmcnt(13)
	v_add_u32_e32 v25, v25, v1
	s_waitcnt vmcnt(12)
	v_add_u32_e32 v25, v25, v3
	s_waitcnt vmcnt(11)
	v_add_u32_e32 v25, v25, v12
	s_waitcnt vmcnt(10)
	v_add_u32_e32 v25, v25, v13
	s_waitcnt vmcnt(9)
	v_add_u32_e32 v25, v25, v14
	s_waitcnt vmcnt(8)
	v_add_u32_e32 v25, v25, v15
	s_waitcnt vmcnt(7)
	v_add_u32_e32 v25, v25, v16
	s_waitcnt vmcnt(6)
	v_add_u32_e32 v25, v25, v17
	s_waitcnt vmcnt(5)
	v_add_u32_e32 v25, v25, v18
	s_waitcnt vmcnt(4)
	v_add_u32_e32 v25, v25, v19
	s_waitcnt vmcnt(3)
	v_add_u32_e32 v25, v25, v20
	s_waitcnt vmcnt(2)
	v_add_u32_e32 v25, v25, v21
	s_waitcnt vmcnt(1)
	v_add_u32_e32 v25, v25, v22
	s_waitcnt vmcnt(0)
	v_add_u32_e32 v25, v25, v23
	v_cmp_eq_u32_e32 vcc, s4, v25
	s_cbranch_vccnz .LBB0_1478
	s_and_b32 s10, s16, 0xff
	s_cmp_eq_u32 s10, 0
	s_mov_b64 s[10:11], -1
	s_mov_b64 s[14:15], -1
	s_sleep 0
	s_cbranch_scc1 .LBB0_1483
	s_and_b64 vcc, exec, s[14:15]
	s_cbranch_vccz .LBB0_1478

; DI unsigned xb_ld(unsigned* p)              { return __hip_atomic_load(p, __ATOMIC_RELAXED, __HIP_MEMORY_SCOPE_AGENT); }
; #define XB_SPIN(cond, bar) do { unsigned _sp = 0; while (cond) { __builtin_amdgcn_s_sleep(1); \
;     if ((++_sp & 255u) == 0u) { if (xb_ld(&(bar)[XB_TMO])) break; if (_sp > XB_SPIN_CAP) { atomicAdd(&(bar)[XB_TMO], 1u); break; } } } } while (0)
; DI void xcd_barrier(const XcdBarrier& b) {
;     ...
;             else XB_SPIN(xb_ld(&bar[XB_TOPGEN]) == tg, bar);
.LBB0_1493:
	s_and_b32 s78, s66, 0xff
	s_mov_b64 s[84:85], -1
	s_cmp_lg_u32 s78, 0
	s_mov_b64 s[88:89], -1
	s_sleep 0
	s_cbranch_scc0 .LBB0_1496
	s_and_b64 vcc, exec, s[88:89]
	s_cbranch_vccz .LBB0_1492

; DI unsigned xb_ld(unsigned* p)              { return __hip_atomic_load(p, __ATOMIC_RELAXED, __HIP_MEMORY_SCOPE_AGENT); }
; DI void xcd_barrier_complete(unsigned* bar, unsigned x, unsigned& nloc, unsigned& nx) {
;     const unsigned G = gridDim.x * gridDim.y * gridDim.z;
;     unsigned sum, cnt, mine, sp = 0u;
;     for (;;) {
;         sum = 0u; cnt = 0u; mine = 0u;
; #pragma unroll
;         for (unsigned j = 0; j < 16; ++j) { const unsigned c = xb_ld(&bar[XB_XCNT(j)]); sum += c; cnt += (c > 0u) ? 1u : 0u; mine = (j == x) ? c : mine; }
;         if (sum == G) break;
;         __builtin_amdgcn_s_sleep(1);
;         if ((++sp & 255u) == 0u) { if (xb_ld(&bar[XB_TMO])) break; if (sp > XB_SPIN_CAP) { atomicAdd(&bar[XB_TMO], 1u); break; } }
;     }
.LBB0_1930:
	global_load_dword v15, v16, s[94:95] offset:1024 sc1
	s_waitcnt lgkmcnt(0)
	global_load_dword v0, v16, s[94:95] offset:1280 sc1
	global_load_dword v1, v16, s[94:95] offset:1536 sc1
	global_load_dword v2, v16, s[94:95] offset:1792 sc1
	global_load_dword v3, v16, s[94:95] offset:2048 sc1
	global_load_dword v4, v16, s[94:95] offset:2304 sc1
	global_load_dword v5, v16, s[94:95] offset:2560 sc1
	global_load_dword v6, v16, s[94:95] offset:2816 sc1
	global_load_dword v7, v16, s[94:95] offset:3072 sc1
	global_load_dword v8, v16, s[94:95] offset:3328 sc1
	global_load_dword v9, v16, s[94:95] offset:3584 sc1
	global_load_dword v10, v16, s[94:95] offset:3840 sc1
	global_load_dword v11, v16, s[2:3] sc1
	global_load_dword v12, v16, s[4:5] sc1
	global_load_dword v13, v16, s[6:7] sc1
	global_load_dword v14, v16, s[8:9] sc1
	s_mov_b64 s[10:11], -1
	s_mov_b64 s[12:13], -1
	s_waitcnt vmcnt(14)
	v_add_u32_e32 v17, v0, v15
	s_waitcnt vmcnt(13)
	v_add_u32_e32 v17, v17, v1
	s_waitcnt vmcnt(12)
	v_add_u32_e32 v17, v17, v2
	s_waitcnt vmcnt(11)
	v_add_u32_e32 v17, v17, v3
	s_waitcnt vmcnt(10)
	v_add_u32_e32 v17, v17, v4
	s_waitcnt vmcnt(9)
	v_add_u32_e32 v17, v17, v5
	s_waitcnt vmcnt(8)
	v_add_u32_e32 v17, v17, v6
	s_waitcnt vmcnt(7)
	v_add_u32_e32 v17, v17, v7
	s_waitcnt vmcnt(6)
	v_add_u32_e32 v17, v17, v8
	s_waitcnt vmcnt(5)
	v_add_u32_e32 v17, v17, v9
	s_waitcnt vmcnt(4)
	v_add_u32_e32 v17, v17, v10
	s_waitcnt vmcnt(3)
	v_add_u32_e32 v17, v17, v11
	s_waitcnt vmcnt(2)
	v_add_u32_e32 v17, v17, v12
	s_waitcnt vmcnt(1)
	v_add_u32_e32 v17, v17, v13
	s_waitcnt vmcnt(0)
	v_add_u32_e32 v17, v17, v14
	v_cmp_eq_u32_e32 vcc, s16, v17
	s_cbranch_vccnz .LBB0_1929
	s_and_b32 s10, s17, 0xff
	s_cmp_eq_u32 s10, 0
	s_mov_b64 s[10:11], -1
	s_mov_b64 s[14:15], -1
	s_sleep 0
	s_cbranch_scc1 .LBB0_1934
	s_and_b64 vcc, exec, s[14:15]
	s_cbranch_vccz .LBB0_1929

; DI unsigned xb_ld(unsigned* p)              { return __hip_atomic_load(p, __ATOMIC_RELAXED, __HIP_MEMORY_SCOPE_AGENT); }
; #define XB_SPIN(cond, bar) do { unsigned _sp = 0; while (cond) { __builtin_amdgcn_s_sleep(1); \
;     if ((++_sp & 255u) == 0u) { if (xb_ld(&(bar)[XB_TMO])) break; if (_sp > XB_SPIN_CAP) { atomicAdd(&(bar)[XB_TMO], 1u); break; } } } } while (0)
; DI void xcd_barrier(const XcdBarrier& b) {
;     ...
;             else XB_SPIN(xb_ld(&bar[XB_TOPGEN]) == tg, bar);
.LBB0_1944:
	s_and_b32 s16, s20, 0xff
	s_mov_b64 s[14:15], -1
	s_cmp_lg_u32 s16, 0
	s_mov_b64 s[18:19], -1
	s_sleep 0
	s_cbranch_scc0 .LBB0_1947
	s_and_b64 vcc, exec, s[18:19]
	s_cbranch_vccz .LBB0_1943

; DI unsigned xb_ld(unsigned* p)              { return __hip_atomic_load(p, __ATOMIC_RELAXED, __HIP_MEMORY_SCOPE_AGENT); }
; #define XB_SPIN(cond, bar) do { unsigned _sp = 0; while (cond) { __builtin_amdgcn_s_sleep(1); \
;     if ((++_sp & 255u) == 0u) { if (xb_ld(&(bar)[XB_TMO])) break; if (_sp > XB_SPIN_CAP) { atomicAdd(&(bar)[XB_TMO], 1u); break; } } } } while (0)
; DI void xcd_barrier(const XcdBarrier& b) {
;     ...
;             XB_SPIN(xb_ld(&bar[XB_XGEN(b.x)]) == gen, bar);
.LBB0_1958:
	s_and_b32 s16, s22, 0xff
	s_cmp_lg_u32 s16, 0
	s_mov_b64 s[18:19], -1
	s_sleep 0
	s_cbranch_scc0 .LBB0_1961
	s_mov_b64 s[20:21], -1
	s_and_b64 vcc, exec, s[18:19]
	s_cbranch_vccz .LBB0_1957
